# gMLP epilogue: GU read-modify-write as 8 dwordx4 loads + 8 dwordx4 stores with v_permlane16_swap (was 16+16 dwordx2)
# baseline (speedup 1.0000x reference)
.LBB0_377:
	s_or_b64 exec, exec, s[22:23]
	s_lshl_b64 s[22:23], s[6:7], 2
	s_add_u32 s9, s26, s22
	s_addc_u32 s25, s27, s23
	s_and_b32 s2, s0, 3
	s_lshl_b32 s3, s2, 9
	s_add_u32 s26, s9, s3
	s_addc_u32 s27, s25, 0
	s_ashr_i32 s25, s24, 31
	s_lshl_b64 s[24:25], s[24:25], 17
	s_add_u32 s9, s12, s24
	s_addc_u32 s25, s13, s25
	s_lshl_b32 s31, s2, 15
	s_add_u32 s24, s9, s31
	s_addc_u32 s25, s25, 0
	v_lshlrev_b32_e32 v1, 3, v0
	v_ashrrev_i32_e32 v22, 3, v0
	s_add_u32 s34, s12, s31
	v_and_b32_e32 v4, 56, v1
	s_addc_u32 s35, s13, 0
	v_lshlrev_b32_e32 v144, 1, v4
	v_lshrrev_b32_e32 v1, 1, v22
	v_lshl_add_u64 v[2:3], s[34:35], 0, v[144:145]
	s_mov_b64 s[34:35], 0x39c0000
	v_xor_b32_e32 v0, v1, v0
	v_ashrrev_i32_e32 v23, 31, v22
	v_lshl_add_u64 v[26:27], v[2:3], 0, s[34:35]
	v_lshlrev_b32_e32 v0, 4, v0
	v_lshlrev_b64 v[8:9], 8, v[22:23]
	v_and_b32_e32 v34, 0x70, v0
	v_lshl_add_u64 v[0:1], s[24:25], 0, v[144:145]
	v_lshl_add_u32 v31, v4, 2, s28
	v_lshl_add_u64 v[10:11], v[26:27], 0, v[8:9]
	s_waitcnt lgkmcnt(0)
	s_barrier
	v_lshl_add_u64 v[18:19], v[0:1], 0, s[68:69]
	ds_read_b128 v[4:7], v31
	ds_read_b128 v[0:3], v31 offset:16
	ds_read_b128 v[36:39], v31 offset:256
	ds_read_b128 v[40:43], v31 offset:272
	s_mov_b64 s[98:99], 0x2000
	v_lshl_add_u64 v[58:59], v[22:23], 2, s[26:27]
	v_lshl_add_u64 v[44:45], v[18:19], 0, v[8:9]
	global_load_dword v60, v[58:59], off
	global_load_dword v61, v[58:59], off offset:128
	global_load_dword v62, v[58:59], off offset:256
	global_load_dword v63, v[58:59], off offset:384
	v_lshl_add_u64 v[52:53], v[10:11], 0, s[98:99]
	v_lshl_add_u64 v[46:47], v[44:45], 0, s[98:99]
	v_lshl_add_u64 v[54:55], v[52:53], 0, s[98:99]
	v_lshl_add_u64 v[48:49], v[46:47], 0, s[98:99]
	v_lshl_add_u64 v[56:57], v[54:55], 0, s[98:99]
	v_lshl_add_u64 v[50:51], v[48:49], 0, s[98:99]
	global_load_dwordx4 v[68:71], v[10:11], off
	global_load_dwordx4 v[100:103], v[44:45], off
	global_load_dwordx4 v[76:79], v[52:53], off
	global_load_dwordx4 v[108:111], v[46:47], off
	global_load_dwordx4 v[84:87], v[54:55], off
	global_load_dwordx4 v[116:119], v[48:49], off
	global_load_dwordx4 v[92:95], v[56:57], off
	global_load_dwordx4 v[124:127], v[50:51], off
	global_load_dwordx4 v[72:75], v[10:11], off offset:128
	global_load_dwordx4 v[104:107], v[44:45], off offset:128
	global_load_dwordx4 v[80:83], v[52:53], off offset:128
	global_load_dwordx4 v[112:115], v[46:47], off offset:128
	global_load_dwordx4 v[88:91], v[54:55], off offset:128
	global_load_dwordx4 v[120:123], v[48:49], off offset:128
	global_load_dwordx4 v[96:99], v[56:57], off offset:128
	global_load_dwordx4 v[128:131], v[50:51], off offset:128
	v_lshl_or_b32 v16, v22, 7, v34
	v_add_u32_e32 v30, s60, v16
	v_bfe_u32 v64, v28, 4, 2
	v_and_b32_e32 v29, 15, v28
	s_movk_i32 s9, 0xffc0
	v_and_b32_e32 v65, 64, v28
	v_readlane_b32 s36, v254, 6
	v_readlane_b32 s46, v254, 16
	v_readlane_b32 s47, v254, 17
	s_mov_b64 s[24:25], s[46:47]
	v_lshlrev_b32_e32 v144, 1, v65
	v_readlane_b32 s37, v254, 7
	v_readlane_b32 s38, v254, 8
	v_readlane_b32 s39, v254, 9
	v_readlane_b32 s40, v254, 10
	v_readlane_b32 s41, v254, 11
	v_readlane_b32 s42, v254, 12
	v_readlane_b32 s43, v254, 13
	v_readlane_b32 s44, v254, 14
	v_readlane_b32 s45, v254, 15
	v_readlane_b32 s48, v254, 18
	v_readlane_b32 s49, v254, 19
	v_readlane_b32 s50, v254, 20
	v_readlane_b32 s51, v254, 21
	v_ashrrev_i32_e32 v132, 1, v28
	v_and_or_b32 v66, v132, s9, v29
	v_ashrrev_i32_e32 v67, 31, v66
	s_add_u32 s9, s24, s22
	s_addc_u32 s23, s25, s23
	s_add_u32 s22, s9, s3
	s_addc_u32 s23, s23, 0
	s_lshl_b32 s2, s2, 8
	s_add_u32 s2, s12, s2
	s_addc_u32 s3, s13, 0
	v_lshl_add_u64 v[132:133], s[2:3], 0, v[144:145]
	v_lshlrev_b32_e32 v144, 3, v64
	v_lshl_add_u64 v[146:147], v[66:67], 2, s[22:23]
	v_lshl_add_u64 v[132:133], v[132:133], 0, v[144:145]
	v_add_u32_e32 v134, s8, v66
	s_mov_b64 s[2:3], 0x71e0000
	v_ashrrev_i32_e32 v135, 31, v134
	v_lshl_add_u64 v[132:133], v[132:133], 0, s[2:3]
	v_lshlrev_b64 v[134:135], 10, v[134:135]
	s_mov_b64 s[98:99], 0x4000
	v_lshl_add_u64 v[216:217], v[132:133], 0, v[134:135]
	v_lshl_add_u64 v[218:219], v[216:217], 0, s[98:99]
	v_lshl_add_u64 v[220:221], v[218:219], 0, s[98:99]
	v_lshl_add_u64 v[222:223], v[220:221], 0, s[98:99]
	v_and_b32_e32 v132, 16, v28
	v_mul_u32_u24_e32 v132, 3, v132
	v_lshrrev_b32_e32 v132, 1, v132
	v_mov_b32_e32 v133, 0
	v_lshl_add_u64 v[216:217], v[216:217], 0, v[132:133]
	v_lshl_add_u64 v[218:219], v[218:219], 0, v[132:133]
	v_lshl_add_u64 v[220:221], v[220:221], 0, v[132:133]
	v_lshl_add_u64 v[222:223], v[222:223], 0, v[132:133]
	global_load_dword v186, v[146:147], off
	global_load_dword v188, v[146:147], off offset:64
	global_load_dword v206, v[146:147], off offset:128
	global_load_dword v208, v[146:147], off offset:192
	global_load_dwordx4 v[154:157], v[216:217], off
	global_load_dwordx4 v[158:161], v[216:217], off offset:64
	global_load_dwordx4 v[162:165], v[218:219], off
	global_load_dwordx4 v[166:169], v[218:219], off offset:64
	global_load_dwordx4 v[170:173], v[220:221], off
	global_load_dwordx4 v[174:177], v[220:221], off offset:64
	global_load_dwordx4 v[178:181], v[222:223], off
	global_load_dwordx4 v[182:185], v[222:223], off offset:64
	s_waitcnt vmcnt(26) lgkmcnt(0)
	ds_write_b128 v30, v[68:71]
	v_lshlrev_b32_e32 v132, 16, v100
	v_and_b32_e32 v133, 0xffff0000, v100
	v_mul_f32_e32 v132, v4, v132
	v_mul_f32_e32 v133, v5, v133
	v_mul_f32_e32 v132, v132, v60
	v_mul_f32_e32 v133, v133, v60
	v_cvt_pk_bf16_f32 v100, v132, v133
	v_lshlrev_b32_e32 v134, 16, v101
	v_and_b32_e32 v135, 0xffff0000, v101
	v_mul_f32_e32 v134, v6, v134
	v_mul_f32_e32 v135, v7, v135
	v_mul_f32_e32 v134, v134, v60
	v_mul_f32_e32 v135, v135, v60
	v_cvt_pk_bf16_f32 v101, v134, v135
	v_lshlrev_b32_e32 v132, 16, v102
	v_and_b32_e32 v133, 0xffff0000, v102
	v_mul_f32_e32 v132, v0, v132
	v_mul_f32_e32 v133, v1, v133
	v_mul_f32_e32 v132, v132, v60
	v_mul_f32_e32 v133, v133, v60
	v_cvt_pk_bf16_f32 v102, v132, v133
	v_lshlrev_b32_e32 v134, 16, v103
	v_and_b32_e32 v135, 0xffff0000, v103
	v_mul_f32_e32 v134, v2, v134
	v_mul_f32_e32 v135, v3, v135
	v_mul_f32_e32 v134, v134, v60
	v_mul_f32_e32 v135, v135, v60
	v_cvt_pk_bf16_f32 v103, v134, v135
	ds_write_b128 v30, v[100:103] offset:16384
	s_waitcnt vmcnt(24)
	ds_write_b128 v30, v[76:79] offset:4096
	v_lshlrev_b32_e32 v132, 16, v108
	v_and_b32_e32 v133, 0xffff0000, v108
	v_mul_f32_e32 v132, v4, v132
	v_mul_f32_e32 v133, v5, v133
	v_mul_f32_e32 v132, v132, v61
	v_mul_f32_e32 v133, v133, v61
	v_cvt_pk_bf16_f32 v108, v132, v133
	v_lshlrev_b32_e32 v134, 16, v109
	v_and_b32_e32 v135, 0xffff0000, v109
	v_mul_f32_e32 v134, v6, v134
	v_mul_f32_e32 v135, v7, v135
	v_mul_f32_e32 v134, v134, v61
	v_mul_f32_e32 v135, v135, v61
	v_cvt_pk_bf16_f32 v109, v134, v135
	v_lshlrev_b32_e32 v132, 16, v110
	v_and_b32_e32 v133, 0xffff0000, v110
	v_mul_f32_e32 v132, v0, v132
	v_mul_f32_e32 v133, v1, v133
	v_mul_f32_e32 v132, v132, v61
	v_mul_f32_e32 v133, v133, v61
	v_cvt_pk_bf16_f32 v110, v132, v133
	v_lshlrev_b32_e32 v134, 16, v111
	v_and_b32_e32 v135, 0xffff0000, v111
	v_mul_f32_e32 v134, v2, v134
	v_mul_f32_e32 v135, v3, v135
	v_mul_f32_e32 v134, v134, v61
	v_mul_f32_e32 v135, v135, v61
	v_cvt_pk_bf16_f32 v111, v134, v135
	ds_write_b128 v30, v[108:111] offset:20480
	s_waitcnt vmcnt(22)
	ds_write_b128 v30, v[84:87] offset:8192
	v_lshlrev_b32_e32 v132, 16, v116
	v_and_b32_e32 v133, 0xffff0000, v116
	v_mul_f32_e32 v132, v4, v132
	v_mul_f32_e32 v133, v5, v133
	v_mul_f32_e32 v132, v132, v62
	v_mul_f32_e32 v133, v133, v62
	v_cvt_pk_bf16_f32 v116, v132, v133
	v_lshlrev_b32_e32 v134, 16, v117
	v_and_b32_e32 v135, 0xffff0000, v117
	v_mul_f32_e32 v134, v6, v134
	v_mul_f32_e32 v135, v7, v135
	v_mul_f32_e32 v134, v134, v62
	v_mul_f32_e32 v135, v135, v62
	v_cvt_pk_bf16_f32 v117, v134, v135
	v_lshlrev_b32_e32 v132, 16, v118
	v_and_b32_e32 v133, 0xffff0000, v118
	v_mul_f32_e32 v132, v0, v132
	v_mul_f32_e32 v133, v1, v133
	v_mul_f32_e32 v132, v132, v62
	v_mul_f32_e32 v133, v133, v62
	v_cvt_pk_bf16_f32 v118, v132, v133
	v_lshlrev_b32_e32 v134, 16, v119
	v_and_b32_e32 v135, 0xffff0000, v119
	v_mul_f32_e32 v134, v2, v134
	v_mul_f32_e32 v135, v3, v135
	v_mul_f32_e32 v134, v134, v62
	v_mul_f32_e32 v135, v135, v62
	v_cvt_pk_bf16_f32 v119, v134, v135
	ds_write_b128 v30, v[116:119] offset:24576
	s_waitcnt vmcnt(20)
	ds_write_b128 v30, v[92:95] offset:12288
	v_lshlrev_b32_e32 v132, 16, v124
	v_and_b32_e32 v133, 0xffff0000, v124
	v_mul_f32_e32 v132, v4, v132
	v_mul_f32_e32 v133, v5, v133
	v_mul_f32_e32 v132, v132, v63
	v_mul_f32_e32 v133, v133, v63
	v_cvt_pk_bf16_f32 v124, v132, v133
	v_lshlrev_b32_e32 v134, 16, v125
	v_and_b32_e32 v135, 0xffff0000, v125
	v_mul_f32_e32 v134, v6, v134
	v_mul_f32_e32 v135, v7, v135
	v_mul_f32_e32 v134, v134, v63
	v_mul_f32_e32 v135, v135, v63
	v_cvt_pk_bf16_f32 v125, v134, v135
	v_lshlrev_b32_e32 v132, 16, v126
	v_and_b32_e32 v133, 0xffff0000, v126
	v_mul_f32_e32 v132, v0, v132
	v_mul_f32_e32 v133, v1, v133
	v_mul_f32_e32 v132, v132, v63
	v_mul_f32_e32 v133, v133, v63
	v_cvt_pk_bf16_f32 v126, v132, v133
	v_lshlrev_b32_e32 v134, 16, v127
	v_and_b32_e32 v135, 0xffff0000, v127
	v_mul_f32_e32 v134, v2, v134
	v_mul_f32_e32 v135, v3, v135
	v_mul_f32_e32 v134, v134, v63
	v_mul_f32_e32 v135, v135, v63
	v_cvt_pk_bf16_f32 v127, v134, v135
	ds_write_b128 v30, v[124:127] offset:28672
	s_waitcnt vmcnt(18)
	ds_write_b128 v30, v[72:75] offset:32768
	v_lshlrev_b32_e32 v132, 16, v104
	v_and_b32_e32 v133, 0xffff0000, v104
	v_mul_f32_e32 v132, v36, v132
	v_mul_f32_e32 v133, v37, v133
	v_mul_f32_e32 v132, v132, v60
	v_mul_f32_e32 v133, v133, v60
	v_cvt_pk_bf16_f32 v104, v132, v133
	v_lshlrev_b32_e32 v134, 16, v105
	v_and_b32_e32 v135, 0xffff0000, v105
	v_mul_f32_e32 v134, v38, v134
	v_mul_f32_e32 v135, v39, v135
	v_mul_f32_e32 v134, v134, v60
	v_mul_f32_e32 v135, v135, v60
	v_cvt_pk_bf16_f32 v105, v134, v135
	v_lshlrev_b32_e32 v132, 16, v106
	v_and_b32_e32 v133, 0xffff0000, v106
	v_mul_f32_e32 v132, v40, v132
	v_mul_f32_e32 v133, v41, v133
	v_mul_f32_e32 v132, v132, v60
	v_mul_f32_e32 v133, v133, v60
	v_cvt_pk_bf16_f32 v106, v132, v133
	v_lshlrev_b32_e32 v134, 16, v107
	v_and_b32_e32 v135, 0xffff0000, v107
	v_mul_f32_e32 v134, v42, v134
	v_mul_f32_e32 v135, v43, v135
	v_mul_f32_e32 v134, v134, v60
	v_mul_f32_e32 v135, v135, v60
	v_cvt_pk_bf16_f32 v107, v134, v135
	ds_write_b128 v30, v[104:107] offset:49152
	s_waitcnt vmcnt(16)
	ds_write_b128 v30, v[80:83] offset:36864
	v_lshlrev_b32_e32 v132, 16, v112
	v_and_b32_e32 v133, 0xffff0000, v112
	v_mul_f32_e32 v132, v36, v132
	v_mul_f32_e32 v133, v37, v133
	v_mul_f32_e32 v132, v132, v61
	v_mul_f32_e32 v133, v133, v61
	v_cvt_pk_bf16_f32 v112, v132, v133
	v_lshlrev_b32_e32 v134, 16, v113
	v_and_b32_e32 v135, 0xffff0000, v113
	v_mul_f32_e32 v134, v38, v134
	v_mul_f32_e32 v135, v39, v135
	v_mul_f32_e32 v134, v134, v61
	v_mul_f32_e32 v135, v135, v61
	v_cvt_pk_bf16_f32 v113, v134, v135
	v_lshlrev_b32_e32 v132, 16, v114
	v_and_b32_e32 v133, 0xffff0000, v114
	v_mul_f32_e32 v132, v40, v132
	v_mul_f32_e32 v133, v41, v133
	v_mul_f32_e32 v132, v132, v61
	v_mul_f32_e32 v133, v133, v61
	v_cvt_pk_bf16_f32 v114, v132, v133
	v_lshlrev_b32_e32 v134, 16, v115
	v_and_b32_e32 v135, 0xffff0000, v115
	v_mul_f32_e32 v134, v42, v134
	v_mul_f32_e32 v135, v43, v135
	v_mul_f32_e32 v134, v134, v61
	v_mul_f32_e32 v135, v135, v61
	v_cvt_pk_bf16_f32 v115, v134, v135
	ds_write_b128 v30, v[112:115] offset:53248
	s_waitcnt vmcnt(14)
	ds_write_b128 v30, v[88:91] offset:40960
	v_lshlrev_b32_e32 v132, 16, v120
	v_and_b32_e32 v133, 0xffff0000, v120
	v_mul_f32_e32 v132, v36, v132
	v_mul_f32_e32 v133, v37, v133
	v_mul_f32_e32 v132, v132, v62
	v_mul_f32_e32 v133, v133, v62
	v_cvt_pk_bf16_f32 v120, v132, v133
	v_lshlrev_b32_e32 v134, 16, v121
	v_and_b32_e32 v135, 0xffff0000, v121
	v_mul_f32_e32 v134, v38, v134
	v_mul_f32_e32 v135, v39, v135
	v_mul_f32_e32 v134, v134, v62
	v_mul_f32_e32 v135, v135, v62
	v_cvt_pk_bf16_f32 v121, v134, v135
	v_lshlrev_b32_e32 v132, 16, v122
	v_and_b32_e32 v133, 0xffff0000, v122
	v_mul_f32_e32 v132, v40, v132
	v_mul_f32_e32 v133, v41, v133
	v_mul_f32_e32 v132, v132, v62
	v_mul_f32_e32 v133, v133, v62
	v_cvt_pk_bf16_f32 v122, v132, v133
	v_lshlrev_b32_e32 v134, 16, v123
	v_and_b32_e32 v135, 0xffff0000, v123
	v_mul_f32_e32 v134, v42, v134
	v_mul_f32_e32 v135, v43, v135
	v_mul_f32_e32 v134, v134, v62
	v_mul_f32_e32 v135, v135, v62
	v_cvt_pk_bf16_f32 v123, v134, v135
	ds_write_b128 v30, v[120:123] offset:57344
	s_waitcnt vmcnt(12)
	ds_write_b128 v30, v[96:99] offset:45056
	v_lshlrev_b32_e32 v132, 16, v128
	v_and_b32_e32 v133, 0xffff0000, v128
	v_mul_f32_e32 v132, v36, v132
	v_mul_f32_e32 v133, v37, v133
	v_mul_f32_e32 v132, v132, v63
	v_mul_f32_e32 v133, v133, v63
	v_cvt_pk_bf16_f32 v128, v132, v133
	v_lshlrev_b32_e32 v134, 16, v129
	v_and_b32_e32 v135, 0xffff0000, v129
	v_mul_f32_e32 v134, v38, v134
	v_mul_f32_e32 v135, v39, v135
	v_mul_f32_e32 v134, v134, v63
	v_mul_f32_e32 v135, v135, v63
	v_cvt_pk_bf16_f32 v129, v134, v135
	v_lshlrev_b32_e32 v132, 16, v130
	v_and_b32_e32 v133, 0xffff0000, v130
	v_mul_f32_e32 v132, v40, v132
	v_mul_f32_e32 v133, v41, v133
	v_mul_f32_e32 v132, v132, v63
	v_mul_f32_e32 v133, v133, v63
	v_cvt_pk_bf16_f32 v130, v132, v133
	v_lshlrev_b32_e32 v134, 16, v131
	v_and_b32_e32 v135, 0xffff0000, v131
	v_mul_f32_e32 v134, v42, v134
	v_mul_f32_e32 v135, v43, v135
	v_mul_f32_e32 v134, v134, v63
	v_mul_f32_e32 v135, v135, v63
	v_cvt_pk_bf16_f32 v131, v134, v135
	ds_write_b128 v30, v[128:131] offset:61440
	v_lshrrev_b32_e32 v1, 1, v28
	v_bfe_u32 v2, v28, 1, 3
	v_bitop3_b32 v1, v1, v64, 7 bitop3:0x6c
	v_bitop3_b32 v2, v64, v2, 4 bitop3:0x36
	v_lshlrev_b32_e32 v0, 7, v66
	v_lshlrev_b32_e32 v1, 4, v1
	v_lshlrev_b32_e32 v2, 4, v2
	v_or_b32_e32 v3, v1, v0
	v_or_b32_e32 v67, v2, v0
	v_lshlrev_b32_e32 v0, 7, v28
	v_and_b32_e32 v0, 0x2780, v0
	v_or_b32_e32 v16, v1, v0
	v_add_u32_e32 v100, s60, v3
	v_add_u32_e32 v101, s60, v16
	s_waitcnt lgkmcnt(0)
	s_barrier
	v_or_b32_e32 v84, v2, v0
	ds_read_b128 v[0:3], v100
	ds_read_b128 v[4:7], v100 offset:2048
	ds_read_b128 v[8:11], v100 offset:4096
	ds_read_b128 v[12:15], v100 offset:6144
	ds_read_b128 v[16:19], v101 offset:16384
	ds_read_b128 v[20:23], v101 offset:18432
	ds_read_b128 v[24:27], v101 offset:20480
	ds_read_b128 v[28:31], v101 offset:22528
	v_add_u32_e32 v67, s60, v67
	v_add_u32_e32 v124, s60, v84
	s_waitcnt lgkmcnt(3)
	v_mfma_f32_16x16x32_bf16 v[32:35], v[16:19], v[0:3], 0
	s_waitcnt lgkmcnt(2)
	v_mfma_f32_16x16x32_bf16 v[36:39], v[20:23], v[0:3], 0
	s_waitcnt lgkmcnt(1)
	v_mfma_f32_16x16x32_bf16 v[40:43], v[24:27], v[0:3], 0
	s_waitcnt lgkmcnt(0)
	v_mfma_f32_16x16x32_bf16 v[0:3], v[28:31], v[0:3], 0
	v_mfma_f32_16x16x32_bf16 v[44:47], v[16:19], v[4:7], 0
	v_mfma_f32_16x16x32_bf16 v[48:51], v[20:23], v[4:7], 0
	v_mfma_f32_16x16x32_bf16 v[52:55], v[24:27], v[4:7], 0
	v_mfma_f32_16x16x32_bf16 v[4:7], v[28:31], v[4:7], 0
	v_mfma_f32_16x16x32_bf16 v[56:59], v[16:19], v[8:11], 0
	v_mfma_f32_16x16x32_bf16 v[60:63], v[20:23], v[8:11], 0
	v_mfma_f32_16x16x32_bf16 v[68:71], v[24:27], v[8:11], 0
	v_mfma_f32_16x16x32_bf16 v[8:11], v[28:31], v[8:11], 0
	v_mfma_f32_16x16x32_bf16 v[16:19], v[16:19], v[12:15], 0
	v_mfma_f32_16x16x32_bf16 v[20:23], v[20:23], v[12:15], 0
	v_mfma_f32_16x16x32_bf16 v[24:27], v[24:27], v[12:15], 0
	v_mfma_f32_16x16x32_bf16 v[12:15], v[28:31], v[12:15], 0
	ds_read_b128 v[28:31], v67
	ds_read_b128 v[72:75], v67 offset:2048
	ds_read_b128 v[76:79], v67 offset:4096
	ds_read_b128 v[80:83], v67 offset:6144
	ds_read_b128 v[84:87], v124 offset:16384
	ds_read_b128 v[88:91], v124 offset:18432
	ds_read_b128 v[92:95], v124 offset:20480
	ds_read_b128 v[96:99], v124 offset:22528
	s_waitcnt lgkmcnt(3)
	v_mfma_f32_16x16x32_bf16 v[32:35], v[84:87], v[28:31], v[32:35]
	s_waitcnt lgkmcnt(2)
	v_mfma_f32_16x16x32_bf16 v[36:39], v[88:91], v[28:31], v[36:39]
	s_waitcnt lgkmcnt(1)
	v_mfma_f32_16x16x32_bf16 v[40:43], v[92:95], v[28:31], v[40:43]
	s_waitcnt lgkmcnt(0)
	v_mfma_f32_16x16x32_bf16 v[0:3], v[96:99], v[28:31], v[0:3]
	v_mfma_f32_16x16x32_bf16 v[28:31], v[84:87], v[72:75], v[44:47]
	v_mfma_f32_16x16x32_bf16 v[44:47], v[88:91], v[72:75], v[48:51]
	v_mfma_f32_16x16x32_bf16 v[48:51], v[92:95], v[72:75], v[52:55]
	v_mfma_f32_16x16x32_bf16 v[4:7], v[96:99], v[72:75], v[4:7]
	v_mfma_f32_16x16x32_bf16 v[52:55], v[84:87], v[76:79], v[56:59]
	v_mfma_f32_16x16x32_bf16 v[56:59], v[88:91], v[76:79], v[60:63]
	v_mfma_f32_16x16x32_bf16 v[60:63], v[92:95], v[76:79], v[68:71]
	v_mfma_f32_16x16x32_bf16 v[8:11], v[96:99], v[76:79], v[8:11]
	v_mfma_f32_16x16x32_bf16 v[16:19], v[84:87], v[80:83], v[16:19]
	v_mfma_f32_16x16x32_bf16 v[20:23], v[88:91], v[80:83], v[20:23]
	v_mfma_f32_16x16x32_bf16 v[24:27], v[92:95], v[80:83], v[24:27]
	v_mfma_f32_16x16x32_bf16 v[12:15], v[96:99], v[80:83], v[12:15]
	ds_read_b128 v[68:71], v100 offset:32768
	ds_read_b128 v[72:75], v100 offset:34816
	ds_read_b128 v[76:79], v100 offset:36864
	ds_read_b128 v[80:83], v100 offset:38912
	ds_read_b128 v[84:87], v101 offset:49152
	ds_read_b128 v[88:91], v101 offset:51200
	ds_read_b128 v[92:95], v101 offset:53248
	ds_read_b128 v[96:99], v101 offset:55296
	s_waitcnt lgkmcnt(3)
	v_mfma_f32_16x16x32_bf16 v[32:35], v[84:87], v[68:71], v[32:35]
	s_waitcnt lgkmcnt(2)
	v_mfma_f32_16x16x32_bf16 v[36:39], v[88:91], v[68:71], v[36:39]
	s_waitcnt lgkmcnt(1)
	v_mfma_f32_16x16x32_bf16 v[40:43], v[92:95], v[68:71], v[40:43]
	s_waitcnt lgkmcnt(0)
	v_mfma_f32_16x16x32_bf16 v[0:3], v[96:99], v[68:71], v[0:3]
	v_mfma_f32_16x16x32_bf16 v[28:31], v[84:87], v[72:75], v[28:31]
	v_mfma_f32_16x16x32_bf16 v[68:71], v[88:91], v[72:75], v[44:47]
	v_mfma_f32_16x16x32_bf16 v[100:103], v[92:95], v[72:75], v[48:51]
	v_mfma_f32_16x16x32_bf16 v[4:7], v[96:99], v[72:75], v[4:7]
	v_mfma_f32_16x16x32_bf16 v[72:75], v[84:87], v[76:79], v[52:55]
	v_mfma_f32_16x16x32_bf16 v[104:107], v[88:91], v[76:79], v[56:59]
	v_mfma_f32_16x16x32_bf16 v[108:111], v[92:95], v[76:79], v[60:63]
	v_mfma_f32_16x16x32_bf16 v[8:11], v[96:99], v[76:79], v[8:11]
	v_mfma_f32_16x16x32_bf16 v[76:79], v[84:87], v[80:83], v[16:19]
	v_mfma_f32_16x16x32_bf16 v[84:87], v[88:91], v[80:83], v[20:23]
	v_mfma_f32_16x16x32_bf16 v[88:91], v[92:95], v[80:83], v[24:27]
	v_mfma_f32_16x16x32_bf16 v[80:83], v[96:99], v[80:83], v[12:15]
	s_nop 2
	ds_read_b128 v[12:15], v67 offset:32768
	ds_read_b128 v[16:19], v67 offset:34816
	ds_read_b128 v[92:95], v67 offset:36864
	ds_read_b128 v[96:99], v67 offset:38912
	ds_read_b128 v[112:115], v124 offset:49152
	ds_read_b128 v[116:119], v124 offset:51200
	ds_read_b128 v[120:123], v124 offset:53248
	ds_read_b128 v[124:127], v124 offset:55296
	s_waitcnt lgkmcnt(0)
	v_mfma_f32_16x16x32_bf16 v[32:35], v[112:115], v[12:15], v[32:35]
	v_mfma_f32_16x16x32_bf16 v[36:39], v[116:119], v[12:15], v[36:39]
	v_mfma_f32_16x16x32_bf16 v[40:43], v[120:123], v[12:15], v[40:43]
	v_mfma_f32_16x16x32_bf16 v[0:3], v[124:127], v[12:15], v[0:3]
	v_mfma_f32_16x16x32_bf16 v[28:31], v[112:115], v[16:19], v[28:31]
	v_mfma_f32_16x16x32_bf16 v[68:71], v[116:119], v[16:19], v[68:71]
	v_mfma_f32_16x16x32_bf16 v[100:103], v[120:123], v[16:19], v[100:103]
	v_mfma_f32_16x16x32_bf16 v[4:7], v[124:127], v[16:19], v[4:7]
	v_mfma_f32_16x16x32_bf16 v[72:75], v[112:115], v[92:95], v[72:75]
	v_mfma_f32_16x16x32_bf16 v[104:107], v[116:119], v[92:95], v[104:107]
	v_mfma_f32_16x16x32_bf16 v[108:111], v[120:123], v[92:95], v[108:111]
	v_mfma_f32_16x16x32_bf16 v[8:11], v[124:127], v[92:95], v[8:11]
	v_mfma_f32_16x16x32_bf16 v[76:79], v[112:115], v[96:99], v[76:79]
	v_mfma_f32_16x16x32_bf16 v[84:87], v[116:119], v[96:99], v[84:87]
	v_mfma_f32_16x16x32_bf16 v[88:91], v[120:123], v[96:99], v[88:91]
	v_mfma_f32_16x16x32_bf16 v[80:83], v[124:127], v[96:99], v[80:83]
	s_waitcnt vmcnt(7)
	v_permlane16_swap_b32 v154, v156
	v_permlane16_swap_b32 v155, v157
	v_pk_add_f32 v[32:33], v[32:33], v[186:187] op_sel_hi:[1,0]
	v_pk_add_f32 v[34:35], v[34:35], v[186:187] op_sel_hi:[1,0]
	v_lshlrev_b32_e32 v132, 16, v154
	v_and_b32_e32 v133, 0xffff0000, v154
	v_lshlrev_b32_e32 v134, 16, v155
	v_and_b32_e32 v135, 0xffff0000, v155
	v_pk_mul_f32 v[32:33], v[32:33], v[132:133]
	v_pk_mul_f32 v[34:35], v[34:35], v[134:135]
	v_cvt_pk_bf16_f32 v154, v32, v33
	v_cvt_pk_bf16_f32 v155, v34, v35
	v_pk_add_f32 v[36:37], v[36:37], v[186:187] op_sel_hi:[1,0]
	v_pk_add_f32 v[38:39], v[38:39], v[186:187] op_sel_hi:[1,0]
	v_lshlrev_b32_e32 v132, 16, v156
	v_and_b32_e32 v133, 0xffff0000, v156
	v_lshlrev_b32_e32 v134, 16, v157
	v_and_b32_e32 v135, 0xffff0000, v157
	v_pk_mul_f32 v[36:37], v[36:37], v[132:133]
	v_pk_mul_f32 v[38:39], v[38:39], v[134:135]
	v_cvt_pk_bf16_f32 v156, v36, v37
	v_cvt_pk_bf16_f32 v157, v38, v39
	s_nop 1
	v_permlane16_swap_b32 v154, v156
	v_permlane16_swap_b32 v155, v157
	global_store_dwordx4 v[216:217], v[154:157], off
	s_waitcnt vmcnt(7)
	v_permlane16_swap_b32 v158, v160
	v_permlane16_swap_b32 v159, v161
	v_pk_add_f32 v[40:41], v[40:41], v[186:187] op_sel_hi:[1,0]
	v_pk_add_f32 v[42:43], v[42:43], v[186:187] op_sel_hi:[1,0]
	v_lshlrev_b32_e32 v132, 16, v158
	v_and_b32_e32 v133, 0xffff0000, v158
	v_lshlrev_b32_e32 v134, 16, v159
	v_and_b32_e32 v135, 0xffff0000, v159
	v_pk_mul_f32 v[40:41], v[40:41], v[132:133]
	v_pk_mul_f32 v[42:43], v[42:43], v[134:135]
	v_cvt_pk_bf16_f32 v158, v40, v41
	v_cvt_pk_bf16_f32 v159, v42, v43
	v_pk_add_f32 v[0:1], v[0:1], v[186:187] op_sel_hi:[1,0]
	v_pk_add_f32 v[2:3], v[2:3], v[186:187] op_sel_hi:[1,0]
	v_lshlrev_b32_e32 v132, 16, v160
	v_and_b32_e32 v133, 0xffff0000, v160
	v_lshlrev_b32_e32 v134, 16, v161
	v_and_b32_e32 v135, 0xffff0000, v161
	v_pk_mul_f32 v[0:1], v[0:1], v[132:133]
	v_pk_mul_f32 v[2:3], v[2:3], v[134:135]
	v_cvt_pk_bf16_f32 v160, v0, v1
	v_cvt_pk_bf16_f32 v161, v2, v3
	s_nop 1
	v_permlane16_swap_b32 v158, v160
	v_permlane16_swap_b32 v159, v161
	global_store_dwordx4 v[216:217], v[158:161], off offset:64
	s_waitcnt vmcnt(7)
	v_permlane16_swap_b32 v162, v164
	v_permlane16_swap_b32 v163, v165
	v_pk_add_f32 v[28:29], v[28:29], v[188:189] op_sel_hi:[1,0]
	v_pk_add_f32 v[30:31], v[30:31], v[188:189] op_sel_hi:[1,0]
	v_lshlrev_b32_e32 v132, 16, v162
	v_and_b32_e32 v133, 0xffff0000, v162
	v_lshlrev_b32_e32 v134, 16, v163
	v_and_b32_e32 v135, 0xffff0000, v163
	v_pk_mul_f32 v[28:29], v[28:29], v[132:133]
	v_pk_mul_f32 v[30:31], v[30:31], v[134:135]
	v_cvt_pk_bf16_f32 v162, v28, v29
	v_cvt_pk_bf16_f32 v163, v30, v31
	v_pk_add_f32 v[68:69], v[68:69], v[188:189] op_sel_hi:[1,0]
	v_pk_add_f32 v[70:71], v[70:71], v[188:189] op_sel_hi:[1,0]
	v_lshlrev_b32_e32 v132, 16, v164
	v_and_b32_e32 v133, 0xffff0000, v164
	v_lshlrev_b32_e32 v134, 16, v165
	v_and_b32_e32 v135, 0xffff0000, v165
	v_pk_mul_f32 v[68:69], v[68:69], v[132:133]
	v_pk_mul_f32 v[70:71], v[70:71], v[134:135]
	v_cvt_pk_bf16_f32 v164, v68, v69
	v_cvt_pk_bf16_f32 v165, v70, v71
	s_nop 1
	v_permlane16_swap_b32 v162, v164
	v_permlane16_swap_b32 v163, v165
	global_store_dwordx4 v[218:219], v[162:165], off
	s_waitcnt vmcnt(7)
	v_permlane16_swap_b32 v166, v168
	v_permlane16_swap_b32 v167, v169
	v_pk_add_f32 v[100:101], v[100:101], v[188:189] op_sel_hi:[1,0]
	v_pk_add_f32 v[102:103], v[102:103], v[188:189] op_sel_hi:[1,0]
	v_lshlrev_b32_e32 v132, 16, v166
	v_and_b32_e32 v133, 0xffff0000, v166
	v_lshlrev_b32_e32 v134, 16, v167
	v_and_b32_e32 v135, 0xffff0000, v167
	v_pk_mul_f32 v[100:101], v[100:101], v[132:133]
	v_pk_mul_f32 v[102:103], v[102:103], v[134:135]
	v_cvt_pk_bf16_f32 v166, v100, v101
	v_cvt_pk_bf16_f32 v167, v102, v103
	v_pk_add_f32 v[4:5], v[4:5], v[188:189] op_sel_hi:[1,0]
	v_pk_add_f32 v[6:7], v[6:7], v[188:189] op_sel_hi:[1,0]
	v_lshlrev_b32_e32 v132, 16, v168
	v_and_b32_e32 v133, 0xffff0000, v168
	v_lshlrev_b32_e32 v134, 16, v169
	v_and_b32_e32 v135, 0xffff0000, v169
	v_pk_mul_f32 v[4:5], v[4:5], v[132:133]
	v_pk_mul_f32 v[6:7], v[6:7], v[134:135]
	v_cvt_pk_bf16_f32 v168, v4, v5
	v_cvt_pk_bf16_f32 v169, v6, v7
	s_nop 1
	v_permlane16_swap_b32 v166, v168
	v_permlane16_swap_b32 v167, v169
	global_store_dwordx4 v[218:219], v[166:169], off offset:64
	s_waitcnt vmcnt(7)
	v_permlane16_swap_b32 v170, v172
	v_permlane16_swap_b32 v171, v173
	v_pk_add_f32 v[72:73], v[72:73], v[206:207] op_sel_hi:[1,0]
	v_pk_add_f32 v[74:75], v[74:75], v[206:207] op_sel_hi:[1,0]
	v_lshlrev_b32_e32 v132, 16, v170
	v_and_b32_e32 v133, 0xffff0000, v170
	v_lshlrev_b32_e32 v134, 16, v171
	v_and_b32_e32 v135, 0xffff0000, v171
	v_pk_mul_f32 v[72:73], v[72:73], v[132:133]
	v_pk_mul_f32 v[74:75], v[74:75], v[134:135]
	v_cvt_pk_bf16_f32 v170, v72, v73
	v_cvt_pk_bf16_f32 v171, v74, v75
	v_pk_add_f32 v[104:105], v[104:105], v[206:207] op_sel_hi:[1,0]
	v_pk_add_f32 v[106:107], v[106:107], v[206:207] op_sel_hi:[1,0]
	v_lshlrev_b32_e32 v132, 16, v172
	v_and_b32_e32 v133, 0xffff0000, v172
	v_lshlrev_b32_e32 v134, 16, v173
	v_and_b32_e32 v135, 0xffff0000, v173
	v_pk_mul_f32 v[104:105], v[104:105], v[132:133]
	v_pk_mul_f32 v[106:107], v[106:107], v[134:135]
	v_cvt_pk_bf16_f32 v172, v104, v105
	v_cvt_pk_bf16_f32 v173, v106, v107
	s_nop 1
	v_permlane16_swap_b32 v170, v172
	v_permlane16_swap_b32 v171, v173
	global_store_dwordx4 v[220:221], v[170:173], off
	s_waitcnt vmcnt(7)
	v_permlane16_swap_b32 v174, v176
	v_permlane16_swap_b32 v175, v177
	v_pk_add_f32 v[108:109], v[108:109], v[206:207] op_sel_hi:[1,0]
	v_pk_add_f32 v[110:111], v[110:111], v[206:207] op_sel_hi:[1,0]
	v_lshlrev_b32_e32 v132, 16, v174
	v_and_b32_e32 v133, 0xffff0000, v174
	v_lshlrev_b32_e32 v134, 16, v175
	v_and_b32_e32 v135, 0xffff0000, v175
	v_pk_mul_f32 v[108:109], v[108:109], v[132:133]
	v_pk_mul_f32 v[110:111], v[110:111], v[134:135]
	v_cvt_pk_bf16_f32 v174, v108, v109
	v_cvt_pk_bf16_f32 v175, v110, v111
	v_pk_add_f32 v[8:9], v[8:9], v[206:207] op_sel_hi:[1,0]
	v_pk_add_f32 v[10:11], v[10:11], v[206:207] op_sel_hi:[1,0]
	v_lshlrev_b32_e32 v132, 16, v176
	v_and_b32_e32 v133, 0xffff0000, v176
	v_lshlrev_b32_e32 v134, 16, v177
	v_and_b32_e32 v135, 0xffff0000, v177
	v_pk_mul_f32 v[8:9], v[8:9], v[132:133]
	v_pk_mul_f32 v[10:11], v[10:11], v[134:135]
	v_cvt_pk_bf16_f32 v176, v8, v9
	v_cvt_pk_bf16_f32 v177, v10, v11
	s_nop 1
	v_permlane16_swap_b32 v174, v176
	v_permlane16_swap_b32 v175, v177
	global_store_dwordx4 v[220:221], v[174:177], off offset:64
	s_waitcnt vmcnt(7)
	v_permlane16_swap_b32 v178, v180
	v_permlane16_swap_b32 v179, v181
	v_pk_add_f32 v[76:77], v[76:77], v[208:209] op_sel_hi:[1,0]
	v_pk_add_f32 v[78:79], v[78:79], v[208:209] op_sel_hi:[1,0]
	v_lshlrev_b32_e32 v132, 16, v178
	v_and_b32_e32 v133, 0xffff0000, v178
	v_lshlrev_b32_e32 v134, 16, v179
	v_and_b32_e32 v135, 0xffff0000, v179
	v_pk_mul_f32 v[76:77], v[76:77], v[132:133]
	v_pk_mul_f32 v[78:79], v[78:79], v[134:135]
	v_cvt_pk_bf16_f32 v178, v76, v77
	v_cvt_pk_bf16_f32 v179, v78, v79
	v_pk_add_f32 v[84:85], v[84:85], v[208:209] op_sel_hi:[1,0]
	v_pk_add_f32 v[86:87], v[86:87], v[208:209] op_sel_hi:[1,0]
	v_lshlrev_b32_e32 v132, 16, v180
	v_and_b32_e32 v133, 0xffff0000, v180
	v_lshlrev_b32_e32 v134, 16, v181
	v_and_b32_e32 v135, 0xffff0000, v181
	v_pk_mul_f32 v[84:85], v[84:85], v[132:133]
	v_pk_mul_f32 v[86:87], v[86:87], v[134:135]
	v_cvt_pk_bf16_f32 v180, v84, v85
	v_cvt_pk_bf16_f32 v181, v86, v87
	s_nop 1
	v_permlane16_swap_b32 v178, v180
	v_permlane16_swap_b32 v179, v181
	global_store_dwordx4 v[222:223], v[178:181], off
	s_waitcnt vmcnt(7)
	v_permlane16_swap_b32 v182, v184
	v_permlane16_swap_b32 v183, v185
	v_pk_add_f32 v[88:89], v[88:89], v[208:209] op_sel_hi:[1,0]
	v_pk_add_f32 v[90:91], v[90:91], v[208:209] op_sel_hi:[1,0]
	v_lshlrev_b32_e32 v132, 16, v182
	v_and_b32_e32 v133, 0xffff0000, v182
	v_lshlrev_b32_e32 v134, 16, v183
	v_and_b32_e32 v135, 0xffff0000, v183
	v_pk_mul_f32 v[88:89], v[88:89], v[132:133]
	v_pk_mul_f32 v[90:91], v[90:91], v[134:135]
	v_cvt_pk_bf16_f32 v182, v88, v89
	v_cvt_pk_bf16_f32 v183, v90, v91
	v_pk_add_f32 v[80:81], v[80:81], v[208:209] op_sel_hi:[1,0]
	v_pk_add_f32 v[82:83], v[82:83], v[208:209] op_sel_hi:[1,0]
	v_lshlrev_b32_e32 v132, 16, v184
	v_and_b32_e32 v133, 0xffff0000, v184
	v_lshlrev_b32_e32 v134, 16, v185
	v_and_b32_e32 v135, 0xffff0000, v185
	v_pk_mul_f32 v[80:81], v[80:81], v[132:133]
	v_pk_mul_f32 v[82:83], v[82:83], v[134:135]
	v_cvt_pk_bf16_f32 v184, v80, v81
	v_cvt_pk_bf16_f32 v185, v82, v83
	s_nop 1
	v_permlane16_swap_b32 v182, v184
	v_permlane16_swap_b32 v183, v185
	global_store_dwordx4 v[222:223], v[182:185], off offset:64
	s_add_i32 s0, s0, s70
	s_cmpk_lt_i32 s0, 0x200
	s_cbranch_scc0 .LBB0_380
